# phase_up: epilogue staging tile in 20 KB of added static LDS beyond the K-loop stages; the units' trailing workgroup barrier removed
# baseline (speedup 1.0000x reference)
.LBB0_917:
	v_mov_b32_e32 v139, v5
	s_movk_i32 s70, 0xa00
	s_movk_i32 s71, 0x50
	v_lshrrev_b32_e32 v186, 6, v5
	v_and_b32_e32 v187, 31, v5
	v_bfe_u32 v188, v5, 5, 1
	v_lshlrev_b32_e32 v188, 3, v188
	v_mad_u32_u24 v182, v186, s70, v188
	v_mad_u32_u24 v182, v187, s71, v182
	v_add_u32_e32 v182, 0x20020, v182
	v_and_b32_e32 v187, 63, v5
	v_lshrrev_b32_e32 v188, 2, v187
	v_and_b32_e32 v187, 3, v187
	v_lshlrev_b32_e32 v187, 4, v187
	v_mad_u32_u24 v183, v186, s70, v187
	v_mad_u32_u24 v183, v188, s71, v183
	v_add_u32_e32 v183, 0x20020, v183
	v_lshl_add_u32 v185, v188, 7, v187
	s_movk_i32 s70, 0xc0
	v_mad_u32_u24 v184, v188, s70, v187
	s_cmpk_gt_i32 s12, 0xbf
	s_mov_b64 s[0:1], -1
	s_cbranch_scc0 .LBB0_967
	s_add_i32 s0, s12, 0xffffff40
	v_ashrrev_i32_e32 v1, 6, v139
	v_bfe_u32 v0, v139, 3, 3
	s_lshr_b32 s68, s0, 2
	v_lshl_or_b32 v0, v1, 3, v0
	s_and_b32 s13, s12, 3
	s_lshl_b64 s[0:1], s[68:69], 16
	v_readlane_b32 s4, v254, 27
	v_lshlrev_b32_e32 v20, 10, v1
	v_lshrrev_b32_e32 v1, 1, v0
	v_readlane_b32 s5, v254, 28
	s_add_u32 s0, s4, s0
	v_xor_b32_e32 v6, v1, v139
	v_ashrrev_i32_e32 v1, 31, v0
	s_addc_u32 s1, s5, s1
	v_add_u32_e32 v21, 32, v20
	v_lshlrev_b64 v[0:1], 8, v[0:1]
	v_lshlrev_b32_e32 v6, 4, v6
	s_lshl_b32 s4, s13, 16
	v_lshl_add_u64 v[2:3], s[0:1], 0, v[0:1]
	v_and_b32_e32 v6, 0x70, v6
	v_mov_b32_e32 v7, v4
	v_readfirstlane_b32 s6, v21
	v_add_u32_e32 v10, 0x8000, v21
	s_add_u32 s4, s10, s4
	v_lshl_add_u64 v[2:3], v[2:3], 0, v[6:7]
	s_mov_b32 m0, s6
	v_readfirstlane_b32 s6, v10
	s_addc_u32 s5, s11, 0
	global_load_lds_dwordx4 v[2:3], off
	s_mov_b32 m0, s6
	s_mov_b64 s[6:7], 0x4000
	v_lshl_add_u64 v[8:9], s[4:5], 0, v[0:1]
	v_add_u32_e32 v14, 0x2000, v21
	v_lshl_add_u64 v[10:11], v[0:1], 0, s[6:7]
	v_lshl_add_u64 v[8:9], v[8:9], 0, v[6:7]
	v_lshl_add_u64 v[12:13], s[0:1], 0, v[10:11]
	v_readfirstlane_b32 s6, v14
	v_add_u32_e32 v14, 0xa000, v21
	global_load_lds_dwordx4 v[8:9], off
	v_lshl_add_u64 v[12:13], v[12:13], 0, v[6:7]
	s_mov_b32 m0, s6
	v_readfirstlane_b32 s6, v14
	global_load_lds_dwordx4 v[12:13], off
	s_mov_b32 m0, s6
	s_mov_b64 s[6:7], 0x8000
	v_lshl_add_u64 v[10:11], s[4:5], 0, v[10:11]
	v_add_u32_e32 v18, 0x4000, v21
	v_lshl_add_u64 v[14:15], v[0:1], 0, s[6:7]
	v_lshl_add_u64 v[10:11], v[10:11], 0, v[6:7]
	v_lshl_add_u64 v[16:17], s[0:1], 0, v[14:15]
	v_readfirstlane_b32 s6, v18
	v_add_u32_e32 v18, 0xc000, v21
	global_load_lds_dwordx4 v[10:11], off
	v_lshl_add_u64 v[16:17], v[16:17], 0, v[6:7]
	s_mov_b32 m0, s6
	v_readfirstlane_b32 s6, v18
	global_load_lds_dwordx4 v[16:17], off
	s_mov_b32 m0, s6
	s_mov_b64 s[6:7], 0xc000
	v_lshl_add_u64 v[0:1], v[0:1], 0, s[6:7]
	v_lshl_add_u64 v[14:15], s[4:5], 0, v[14:15]
	v_add_u32_e32 v22, 0x6000, v21
	v_lshl_add_u64 v[18:19], s[0:1], 0, v[0:1]
	v_lshl_add_u64 v[0:1], s[4:5], 0, v[0:1]
	v_lshl_add_u64 v[14:15], v[14:15], 0, v[6:7]
	v_lshl_add_u64 v[18:19], v[18:19], 0, v[6:7]
	v_readfirstlane_b32 s0, v22
	v_lshl_add_u64 v[0:1], v[0:1], 0, v[6:7]
	v_add_u32_e32 v6, 0xe000, v21
	global_load_lds_dwordx4 v[14:15], off
	s_mov_b32 m0, s0
	v_readfirstlane_b32 s0, v6
	v_lshrrev_b32_e32 v6, 5, v139
	v_bfe_u32 v148, v139, 1, 3
	v_bitop3_b32 v6, v6, v148, 1 bitop3:0x6c
	global_load_lds_dwordx4 v[18:19], off
	s_mov_b32 m0, s0
	v_lshlrev_b32_e32 v149, 4, v6
	v_lshlrev_b32_e32 v6, 7, v139
	s_add_i32 s0, 32, 0x10000
	v_and_b32_e32 v150, 0x6f80, v6
	v_add_u32_e32 v6, s0, v20
	global_load_lds_dwordx4 v[0:1], off
	v_readfirstlane_b32 s1, v6
	v_lshl_add_u64 v[2:3], v[2:3], 0, s[54:55]
	s_mov_b32 m0, s1
	s_waitcnt vmcnt(0)
	s_waitcnt vmcnt(0) lgkmcnt(0)
	s_barrier
	global_load_lds_dwordx4 v[2:3], off
	v_lshl_add_u64 v[2:3], v[8:9], 0, s[54:55]
	v_add_u32_e32 v8, 0x8000, v6
	v_and_b32_e32 v152, 31, v139
	v_readfirstlane_b32 s1, v8
	v_add_u32_e32 v8, 0x2000, v6
	s_mov_b32 m0, s1
	v_readfirstlane_b32 s1, v8
	v_add_u32_e32 v8, 0xa000, v6
	global_load_lds_dwordx4 v[2:3], off
	v_lshl_add_u64 v[2:3], v[12:13], 0, s[54:55]
	s_mov_b32 m0, s1
	v_readfirstlane_b32 s1, v8
	v_add_u32_e32 v8, 0x4000, v6
	global_load_lds_dwordx4 v[2:3], off
	v_lshl_add_u64 v[2:3], v[10:11], 0, s[54:55]
	s_mov_b32 m0, s1
	v_readfirstlane_b32 s1, v8
	v_add_u32_e32 v8, 0xc000, v6
	global_load_lds_dwordx4 v[2:3], off
	v_lshl_add_u64 v[2:3], v[16:17], 0, s[54:55]
	s_mov_b32 m0, s1
	v_readfirstlane_b32 s1, v8
	v_add_u32_e32 v8, 0x6000, v6
	global_load_lds_dwordx4 v[2:3], off
	v_lshl_add_u64 v[2:3], v[14:15], 0, s[54:55]
	s_mov_b32 m0, s1
	v_readfirstlane_b32 s1, v8
	global_load_lds_dwordx4 v[2:3], off
	v_lshl_add_u64 v[2:3], v[18:19], 0, s[54:55]
	s_mov_b32 m0, s1
	v_lshrrev_b32_e32 v7, 1, v139
	global_load_lds_dwordx4 v[2:3], off
	v_add_u32_e32 v2, 0xe000, v6
	v_lshl_add_u64 v[0:1], v[0:1], 0, s[54:55]
	v_readfirstlane_b32 s1, v2
	s_mov_b32 m0, s1
	s_mov_b32 s1, 0x1ffff80
	v_and_or_b32 v7, v7, s1, v152
	v_add_u32_e32 v6, 32, v149
	v_lshlrev_b32_e32 v151, 7, v7
	global_load_lds_dwordx4 v[0:1], off
	v_add_u32_e32 v10, v6, v150
	v_add_u32_e32 v14, v6, v151
	ds_read_b128 v[0:3], v10 offset:32768
	ds_read_b128 v[6:9], v14
	ds_read_b128 v[10:13], v10 offset:36864
	s_waitcnt lgkmcnt(0)
	v_mfma_f32_32x32x16_bf16 v[118:133], v[0:3], v[6:9], 0
	v_bfe_u32 v153, v139, 5, 1
	s_add_i32 s1, 32, 0x18000
	v_mfma_f32_32x32x16_bf16 v[102:117], v[10:13], v[6:9], 0
	ds_read_b128 v[6:9], v14 offset:4096
	s_waitcnt lgkmcnt(0)
	v_mfma_f32_32x32x16_bf16 v[86:101], v[0:3], v[6:9], 0
	v_mfma_f32_32x32x16_bf16 v[70:85], v[10:13], v[6:9], 0
	ds_read_b128 v[6:9], v14 offset:8192
	s_waitcnt lgkmcnt(0)
	v_mfma_f32_32x32x16_bf16 v[54:69], v[0:3], v[6:9], 0
	v_mfma_f32_32x32x16_bf16 v[38:53], v[10:13], v[6:9], 0
	ds_read_b128 v[6:9], v14 offset:12288
	s_waitcnt lgkmcnt(0)
	v_mfma_f32_32x32x16_bf16 v[22:37], v[0:3], v[6:9], 0
	v_bitop3_b32 v0, v153, v148, 2 bitop3:0x36
	v_lshlrev_b32_e32 v154, 4, v0
	v_add_u32_e32 v134, 32, v154
	v_add_u32_e32 v144, v134, v150
	v_add_u32_e32 v155, v134, v151
	ds_read_b128 v[0:3], v144 offset:32768
	ds_read_b128 v[134:137], v155
	ds_read_b128 v[144:147], v144 offset:36864
	s_waitcnt lgkmcnt(0)
	v_mfma_f32_32x32x16_bf16 v[118:133], v[0:3], v[134:137], v[118:133]
	v_mfma_f32_32x32x16_bf16 v[102:117], v[144:147], v[134:137], v[102:117]
	ds_read_b128 v[134:137], v155 offset:4096
	s_waitcnt lgkmcnt(0)
	v_mfma_f32_32x32x16_bf16 v[86:101], v[0:3], v[134:137], v[86:101]
	v_mfma_f32_32x32x16_bf16 v[70:85], v[144:147], v[134:137], v[70:85]
	ds_read_b128 v[134:137], v155 offset:8192
	v_mfma_f32_32x32x16_bf16 v[6:21], v[10:13], v[6:9], 0
	s_waitcnt lgkmcnt(0)
	v_mfma_f32_32x32x16_bf16 v[54:69], v[0:3], v[134:137], v[54:69]
	v_mfma_f32_32x32x16_bf16 v[38:53], v[144:147], v[134:137], v[38:53]
	ds_read_b128 v[134:137], v155 offset:12288
	s_waitcnt lgkmcnt(0)
	v_mfma_f32_32x32x16_bf16 v[22:37], v[0:3], v[134:137], v[22:37]
	v_bitop3_b32 v0, v153, v148, 4 bitop3:0x36
	v_lshlrev_b32_e32 v155, 4, v0
	v_mfma_f32_32x32x16_bf16 v[6:21], v[144:147], v[134:137], v[6:21]
	v_add_u32_e32 v134, 32, v155
	v_add_u32_e32 v144, v134, v150
	v_add_u32_e32 v156, v134, v151
	ds_read_b128 v[0:3], v144 offset:32768
	ds_read_b128 v[134:137], v156
	ds_read_b128 v[144:147], v144 offset:36864
	s_waitcnt lgkmcnt(0)
	v_mfma_f32_32x32x16_bf16 v[118:133], v[0:3], v[134:137], v[118:133]
	v_mfma_f32_32x32x16_bf16 v[102:117], v[144:147], v[134:137], v[102:117]
	ds_read_b128 v[134:137], v156 offset:4096
	s_waitcnt lgkmcnt(0)
	v_mfma_f32_32x32x16_bf16 v[86:101], v[0:3], v[134:137], v[86:101]
	v_mfma_f32_32x32x16_bf16 v[70:85], v[144:147], v[134:137], v[70:85]
	ds_read_b128 v[134:137], v156 offset:8192
	s_waitcnt lgkmcnt(0)
	v_mfma_f32_32x32x16_bf16 v[54:69], v[0:3], v[134:137], v[54:69]
	v_mfma_f32_32x32x16_bf16 v[38:53], v[144:147], v[134:137], v[38:53]
	ds_read_b128 v[134:137], v156 offset:12288
	s_waitcnt lgkmcnt(0)
	v_mfma_f32_32x32x16_bf16 v[22:37], v[0:3], v[134:137], v[22:37]
	v_bitop3_b32 v0, v153, v148, 6 bitop3:0x36
	v_lshlrev_b32_e32 v148, 4, v0
	v_mfma_f32_32x32x16_bf16 v[6:21], v[144:147], v[134:137], v[6:21]
	v_add_u32_e32 v134, 32, v148
	v_add_u32_e32 v144, v134, v150
	v_add_u32_e32 v153, v134, v151
	ds_read_b128 v[0:3], v144 offset:32768
	ds_read_b128 v[134:137], v153
	ds_read_b128 v[144:147], v144 offset:36864
	s_waitcnt lgkmcnt(0)
	v_mfma_f32_32x32x16_bf16 v[118:133], v[0:3], v[134:137], v[118:133]
	v_mfma_f32_32x32x16_bf16 v[102:117], v[144:147], v[134:137], v[102:117]
	ds_read_b128 v[134:137], v153 offset:4096
	s_waitcnt lgkmcnt(0)
	v_mfma_f32_32x32x16_bf16 v[86:101], v[0:3], v[134:137], v[86:101]
	v_mfma_f32_32x32x16_bf16 v[70:85], v[144:147], v[134:137], v[70:85]
	ds_read_b128 v[134:137], v153 offset:8192
	s_waitcnt lgkmcnt(0)
	v_mfma_f32_32x32x16_bf16 v[54:69], v[0:3], v[134:137], v[54:69]
	v_mfma_f32_32x32x16_bf16 v[38:53], v[144:147], v[134:137], v[38:53]
	ds_read_b128 v[134:137], v153 offset:12288
	s_waitcnt vmcnt(0)
	s_waitcnt vmcnt(0) lgkmcnt(0)
	s_barrier
	v_mfma_f32_32x32x16_bf16 v[6:21], v[144:147], v[134:137], v[6:21]
	v_add3_u32 v144, s1, v149, v150
	v_add3_u32 v149, s0, v149, v151
	v_mfma_f32_32x32x16_bf16 v[22:37], v[0:3], v[134:137], v[22:37]
	ds_read_b128 v[0:3], v144
	ds_read_b128 v[134:137], v149
	ds_read_b128 v[144:147], v144 offset:4096
	s_waitcnt lgkmcnt(1)
	v_mfma_f32_32x32x16_bf16 v[118:133], v[0:3], v[134:137], v[118:133]
	s_waitcnt lgkmcnt(0)
	v_mfma_f32_32x32x16_bf16 v[102:117], v[144:147], v[134:137], v[102:117]
	ds_read_b128 v[134:137], v149 offset:4096
	s_waitcnt lgkmcnt(0)
	v_mfma_f32_32x32x16_bf16 v[86:101], v[0:3], v[134:137], v[86:101]
	v_mfma_f32_32x32x16_bf16 v[70:85], v[144:147], v[134:137], v[70:85]
	ds_read_b128 v[134:137], v149 offset:8192
	s_waitcnt lgkmcnt(0)
	v_mfma_f32_32x32x16_bf16 v[54:69], v[0:3], v[134:137], v[54:69]
	v_mfma_f32_32x32x16_bf16 v[38:53], v[144:147], v[134:137], v[38:53]
	ds_read_b128 v[134:137], v149 offset:12288
	v_add3_u32 v149, s0, v154, v151
	s_waitcnt lgkmcnt(0)
	v_mfma_f32_32x32x16_bf16 v[6:21], v[144:147], v[134:137], v[6:21]
	v_add3_u32 v144, s1, v154, v150
	v_mfma_f32_32x32x16_bf16 v[22:37], v[0:3], v[134:137], v[22:37]
	ds_read_b128 v[0:3], v144
	ds_read_b128 v[134:137], v149
	ds_read_b128 v[144:147], v144 offset:4096
	s_waitcnt lgkmcnt(1)
	v_mfma_f32_32x32x16_bf16 v[118:133], v[0:3], v[134:137], v[118:133]
	s_waitcnt lgkmcnt(0)
	v_mfma_f32_32x32x16_bf16 v[102:117], v[144:147], v[134:137], v[102:117]
	ds_read_b128 v[134:137], v149 offset:4096
	s_waitcnt lgkmcnt(0)
	v_mfma_f32_32x32x16_bf16 v[86:101], v[0:3], v[134:137], v[86:101]
	v_mfma_f32_32x32x16_bf16 v[70:85], v[144:147], v[134:137], v[70:85]
	ds_read_b128 v[134:137], v149 offset:8192
	s_waitcnt lgkmcnt(0)
	v_mfma_f32_32x32x16_bf16 v[54:69], v[0:3], v[134:137], v[54:69]
	v_mfma_f32_32x32x16_bf16 v[38:53], v[144:147], v[134:137], v[38:53]
	ds_read_b128 v[134:137], v149 offset:12288
	v_add3_u32 v149, s0, v155, v151
	s_waitcnt lgkmcnt(0)
	v_mfma_f32_32x32x16_bf16 v[6:21], v[144:147], v[134:137], v[6:21]
	v_add3_u32 v144, s1, v155, v150
	v_mfma_f32_32x32x16_bf16 v[22:37], v[0:3], v[134:137], v[22:37]
	ds_read_b128 v[0:3], v144
	ds_read_b128 v[134:137], v149
	ds_read_b128 v[144:147], v144 offset:4096
	s_waitcnt lgkmcnt(1)
	v_mfma_f32_32x32x16_bf16 v[118:133], v[0:3], v[134:137], v[118:133]
	s_waitcnt lgkmcnt(0)
	v_mfma_f32_32x32x16_bf16 v[102:117], v[144:147], v[134:137], v[102:117]
	ds_read_b128 v[134:137], v149 offset:4096
	s_waitcnt lgkmcnt(0)
	v_mfma_f32_32x32x16_bf16 v[86:101], v[0:3], v[134:137], v[86:101]
	v_mfma_f32_32x32x16_bf16 v[70:85], v[144:147], v[134:137], v[70:85]
	ds_read_b128 v[134:137], v149 offset:8192
	s_waitcnt lgkmcnt(0)
	v_mfma_f32_32x32x16_bf16 v[54:69], v[0:3], v[134:137], v[54:69]
	v_mfma_f32_32x32x16_bf16 v[38:53], v[144:147], v[134:137], v[38:53]
	ds_read_b128 v[134:137], v149 offset:12288
	s_waitcnt lgkmcnt(0)
	v_mfma_f32_32x32x16_bf16 v[6:21], v[144:147], v[134:137], v[6:21]
	v_add3_u32 v144, s1, v148, v150
	ds_read_b128 v[154:157], v144 offset:4096
	v_add3_u32 v145, s0, v148, v151
	s_movk_i32 s0, 0x9f
	v_mfma_f32_32x32x16_bf16 v[22:37], v[0:3], v[134:137], v[22:37]
	ds_read_b128 v[0:3], v144
	ds_read_b128 v[134:137], v145
	s_waitcnt lgkmcnt(0)
	v_mfma_f32_32x32x16_bf16 v[118:133], v[0:3], v[134:137], v[118:133]
	v_mfma_f32_32x32x16_bf16 v[102:117], v[154:157], v[134:137], v[102:117]
	ds_read_b128 v[134:137], v145 offset:4096
	ds_read_b128 v[148:151], v145 offset:8192
	ds_read_b128 v[158:161], v145 offset:12288
	s_waitcnt vmcnt(0)
	s_waitcnt lgkmcnt(0)
	v_mfma_f32_32x32x16_bf16 v[86:101], v[0:3], v[134:137], v[86:101]
	v_mfma_f32_32x32x16_bf16 v[70:85], v[154:157], v[134:137], v[70:85]
	v_ashrrev_i32_e32 v134, 1, v139
	v_and_b32_e32 v134, 0xffffff80, v134
	v_or_b32_e32 v135, v134, v152
	v_lshl_add_u32 v144, s68, 8, v135
	v_bitop3_b32 v146, v134, s0, v152 bitop3:0xc8
	v_subrev_co_u32_e32 v134, vcc, 0x4000, v144
	v_mfma_f32_32x32x16_bf16 v[54:69], v[0:3], v[148:151], v[54:69]
	v_lshrrev_b32_e32 v137, 9, v134
	v_and_b32_e32 v134, 0x19f, v144
	v_ashrrev_i32_e32 v136, 8, v144
	s_mov_b64 s[4:5], vcc
	v_cmp_lt_i32_e64 s[6:7], s89, v144
	v_mov_b32_e32 v152, v146
	v_mov_b32_e32 v145, v136
	v_mfma_f32_32x32x16_bf16 v[38:53], v[154:157], v[148:151], v[38:53]
	v_or_b32_e32 v149, 0x1000, v134
	v_add_u32_e32 v134, 0xffffe000, v144
	v_lshrrev_b32_e32 v150, 12, v134
	v_and_b32_e32 v151, 0xf9f, v144
	v_mov_b64_e32 v[134:135], 0xc952000
	v_cndmask_b32_e64 v147, v149, v151, s[4:5]
	v_cndmask_b32_e64 v148, v137, v150, s[4:5]
	v_mfma_f32_32x32x16_bf16 v[22:37], v[0:3], v[158:161], v[22:37]
	v_mov_b64_e32 v[2:3], 0x100
	v_mov_b64_e32 v[0:1], 0xdb62000
	v_mfma_f32_32x32x16_bf16 v[6:21], v[154:157], v[158:161], v[6:21]
	s_and_saveexec_b64 s[0:1], s[6:7]
	v_cndmask_b32_e64 v152, v149, v151, s[4:5]
	v_cndmask_b32_e64 v145, v137, v150, s[4:5]
	v_mov_b64_e32 v[2:3], 0x1200
	v_mov_b64_e32 v[134:135], 0xd152000
	v_mov_b64_e32 v[0:1], 0xe362000
	s_or_b64 exec, exec, s[0:1]
	v_lshrrev_b32_e32 v3, 3, v139
	v_and_b32_e32 v137, 0x80, v139
	v_lshl_or_b32 v137, s13, 8, v137
	v_and_b32_e32 v151, 4, v3
	v_or_b32_e32 v149, 0xffffffc0, v151
	v_lshrrev_b32_e32 v137, 7, v137
	v_and_b32_e32 v150, 64, v139
	v_lshl_or_b32 v3, v145, 3, v137
	v_cmp_ne_u32_e32 vcc, 0, v150
	v_add_u32_e32 v145, v149, v150
	s_and_saveexec_b64 s[0:1], vcc
	s_xor_b64 s[0:1], exec, s[0:1]
	s_cbranch_execz .LBB0_922
	v_mad_i64_i32 v[134:135], s[14:15], v2, v3, 0
	v_lshl_add_u64 v[0:1], s[26:27], 0, v[0:1]
	v_lshlrev_b64 v[134:135], 7, v[134:135]
	v_lshl_add_u64 v[0:1], v[0:1], 0, v[134:135]
	v_mad_u64_u32 v[134:135], s[14:15], v2, v145, 0
	v_lshl_add_u64 v[0:1], v[134:135], 1, v[0:1]
	v_lshlrev_b32_e32 v134, 1, v152
	v_mov_b32_e32 v135, v4
	v_lshl_add_u64 v[0:1], v[0:1], 0, v[134:135]
	v_cvt_pk_bf16_f32 v3, v118, s0
	global_store_short v[0:1], v3, off
	v_cvt_pk_bf16_f32 v3, v119, s0
	v_lshlrev_b32_e32 v118, 1, v2
	v_mov_b32_e32 v119, v4
	v_lshl_add_u64 v[0:1], v[0:1], 0, v[118:119]
	global_store_short v[0:1], v3, off
	v_cvt_pk_bf16_f32 v3, v120, s0
	v_lshl_add_u64 v[0:1], v[0:1], 0, v[118:119]
	global_store_short v[0:1], v3, off
	v_cvt_pk_bf16_f32 v3, v121, s0
	v_lshl_add_u64 v[0:1], v[0:1], 0, v[118:119]
	global_store_short v[0:1], v3, off
	v_cvt_pk_bf16_f32 v3, v122, s0
	v_mad_u64_u32 v[0:1], s[14:15], v2, 10, v[0:1]
	global_store_short v[0:1], v3, off
	v_cvt_pk_bf16_f32 v3, v123, s0
	v_lshl_add_u64 v[0:1], v[0:1], 0, v[118:119]
	global_store_short v[0:1], v3, off
	v_cvt_pk_bf16_f32 v3, v124, s0
	v_lshl_add_u64 v[0:1], v[0:1], 0, v[118:119]
	global_store_short v[0:1], v3, off
	v_cvt_pk_bf16_f32 v3, v125, s0
	v_lshl_add_u64 v[0:1], v[0:1], 0, v[118:119]
	global_store_short v[0:1], v3, off
	v_cvt_pk_bf16_f32 v3, v126, s0
	v_mad_u64_u32 v[0:1], s[14:15], v2, 10, v[0:1]
	global_store_short v[0:1], v3, off
	v_cvt_pk_bf16_f32 v3, v127, s0
	v_lshl_add_u64 v[0:1], v[0:1], 0, v[118:119]
	global_store_short v[0:1], v3, off
	v_cvt_pk_bf16_f32 v3, v128, s0
	v_lshl_add_u64 v[0:1], v[0:1], 0, v[118:119]
	global_store_short v[0:1], v3, off
	v_cvt_pk_bf16_f32 v3, v129, s0
	v_lshl_add_u64 v[0:1], v[0:1], 0, v[118:119]
	global_store_short v[0:1], v3, off
	v_cvt_pk_bf16_f32 v3, v130, s0
	v_mad_u64_u32 v[0:1], s[14:15], v2, 10, v[0:1]
	global_store_short v[0:1], v3, off
	v_cvt_pk_bf16_f32 v2, v131, s0
	v_lshl_add_u64 v[0:1], v[0:1], 0, v[118:119]
	global_store_short v[0:1], v2, off
	v_cvt_pk_bf16_f32 v2, v132, s0
	v_lshl_add_u64 v[0:1], v[0:1], 0, v[118:119]
	global_store_short v[0:1], v2, off
	v_cvt_pk_bf16_f32 v2, v133, s0
	v_lshl_add_u64 v[0:1], v[0:1], 0, v[118:119]
	global_store_short v[0:1], v2, off

.LBB0_967:
	s_and_b64 vcc, exec, s[0:1]
	s_cbranch_vccz .LBB0_916
	s_mul_hi_i32 s0, s12, 0x2aaaaaab
	s_lshr_b32 s1, s0, 31
	s_ashr_i32 s0, s0, 2
	s_add_i32 s0, s0, s1
	s_lshl_b32 s1, s0, 3
	s_and_b32 s4, s12, 7
	s_mulk_i32 s0, 0xffe8
	s_or_b32 s4, s1, s4
	s_add_i32 s0, s12, s0
	s_ashr_i32 s5, s4, 31
	s_ashr_i32 s0, s0, 3
	s_lshl_b64 s[6:7], s[4:5], 17
	v_readlane_b32 s14, v254, 29
	v_ashrrev_i32_e32 v1, 6, v139
	v_bfe_u32 v0, v139, 3, 3
	v_readlane_b32 s15, v254, 30
	s_add_u32 s6, s14, s6
	v_lshl_or_b32 v0, v1, 3, v0
	s_addc_u32 s7, s15, s7
	s_ashr_i32 s1, s0, 31
	v_lshlrev_b32_e32 v14, 10, v1
	v_lshrrev_b32_e32 v1, 1, v0
	s_lshl_b64 s[14:15], s[0:1], 17
	v_xor_b32_e32 v2, v1, v139
	v_add_u32_e32 v15, 32, v14
	v_ashrrev_i32_e32 v1, 31, v0
	s_add_u32 s14, s8, s14
	v_lshlrev_b64 v[6:7], 9, v[0:1]
	v_add_u32_e32 v10, 0x8000, v15
	s_mov_b64 s[16:17], 0x8000
	s_addc_u32 s15, s9, s15
	v_lshlrev_b32_e32 v2, 4, v2
	v_readfirstlane_b32 s19, v10
	v_lshl_add_u64 v[10:11], v[6:7], 0, s[16:17]
	v_and_b32_e32 v8, 0x70, v2
	v_mov_b32_e32 v9, v4
	v_lshl_add_u64 v[12:13], s[6:7], 0, v[10:11]
	v_lshl_add_u64 v[10:11], s[14:15], 0, v[10:11]
	v_lshl_add_u64 v[0:1], s[6:7], 0, v[6:7]
	v_readfirstlane_b32 s18, v15
	v_lshl_add_u64 v[136:137], v[10:11], 0, v[8:9]
	v_add_u32_e32 v10, 0xa000, v15
	s_mov_b64 s[16:17], 0x10000
	v_lshl_add_u64 v[0:1], v[0:1], 0, v[8:9]
	s_mov_b32 m0, s18
	v_lshl_add_u64 v[2:3], s[14:15], 0, v[6:7]
	v_add_u32_e32 v16, 0x2000, v15
	v_readfirstlane_b32 s21, v10
	v_lshl_add_u64 v[10:11], v[6:7], 0, s[16:17]
	global_load_lds_dwordx4 v[0:1], off
	v_lshl_add_u64 v[2:3], v[2:3], 0, v[8:9]
	s_mov_b32 m0, s19
	v_lshl_add_u64 v[134:135], v[12:13], 0, v[8:9]
	v_readfirstlane_b32 s20, v16
	v_lshl_add_u64 v[12:13], s[6:7], 0, v[10:11]
	v_lshl_add_u64 v[10:11], s[14:15], 0, v[10:11]
	s_mov_b64 s[16:17], 0x18000
	global_load_lds_dwordx4 v[2:3], off
	s_mov_b32 m0, s20
	v_add_u32_e32 v16, 0x4000, v15
	v_lshl_add_u64 v[146:147], v[10:11], 0, v[8:9]
	v_add_u32_e32 v10, 0xc000, v15
	v_lshl_add_u64 v[6:7], v[6:7], 0, s[16:17]
	global_load_lds_dwordx4 v[134:135], off
	s_mov_b32 m0, s21
	v_readfirstlane_b32 s22, v16
	v_readfirstlane_b32 s23, v10
	v_lshl_add_u64 v[10:11], s[6:7], 0, v[6:7]
	v_lshl_add_u64 v[6:7], s[14:15], 0, v[6:7]
	global_load_lds_dwordx4 v[136:137], off
	v_lshl_add_u64 v[144:145], v[12:13], 0, v[8:9]
	s_mov_b32 m0, s22
	v_add_u32_e32 v12, 0x6000, v15
	v_lshl_add_u64 v[150:151], v[6:7], 0, v[8:9]
	v_add_u32_e32 v6, 0xe000, v15
	global_load_lds_dwordx4 v[144:145], off
	s_mov_b32 m0, s23
	v_readfirstlane_b32 s35, v12
	v_readfirstlane_b32 s44, v6
	v_lshrrev_b32_e32 v6, 5, v139
	v_bfe_u32 v153, v139, 1, 3
	s_add_i32 s17, 32, 0x10000
	global_load_lds_dwordx4 v[146:147], off
	v_lshl_add_u64 v[148:149], v[10:11], 0, v[8:9]
	s_mov_b32 m0, s35
	v_bitop3_b32 v6, v6, v153, 1 bitop3:0x6c
	v_add_u32_e32 v8, s17, v14
	global_load_lds_dwordx4 v[148:149], off
	s_mov_b32 m0, s44
	v_lshlrev_b32_e32 v166, 4, v6
	v_lshlrev_b32_e32 v6, 7, v139
	v_readfirstlane_b32 s1, v8
	v_add_u32_e32 v9, 0x8000, v8
	global_load_lds_dwordx4 v[150:151], off
	v_and_b32_e32 v167, 0x6f80, v6
	v_lshl_add_u64 v[6:7], v[0:1], 0, s[54:55]
	s_mov_b32 m0, s1
	v_readfirstlane_b32 s5, v9
	v_add_u32_e32 v9, 0x2000, v8
	s_waitcnt vmcnt(0)
	s_waitcnt vmcnt(0) lgkmcnt(0)
	s_barrier
	global_load_lds_dwordx4 v[6:7], off
	v_lshl_add_u64 v[6:7], v[2:3], 0, s[54:55]
	s_mov_b32 m0, s5
	v_readfirstlane_b32 s6, v9
	v_add_u32_e32 v9, 0xa000, v8
	global_load_lds_dwordx4 v[6:7], off
	v_lshl_add_u64 v[6:7], v[134:135], 0, s[54:55]
	s_mov_b32 m0, s6
	v_readfirstlane_b32 s7, v9
	v_add_u32_e32 v9, 0x4000, v8
	global_load_lds_dwordx4 v[6:7], off
	v_lshl_add_u64 v[6:7], v[136:137], 0, s[54:55]
	s_mov_b32 m0, s7
	v_readfirstlane_b32 s13, v9
	v_add_u32_e32 v9, 0xc000, v8
	global_load_lds_dwordx4 v[6:7], off
	v_lshl_add_u64 v[6:7], v[144:145], 0, s[54:55]
	s_mov_b32 m0, s13
	v_readfirstlane_b32 s14, v9
	v_add_u32_e32 v9, 0x6000, v8
	global_load_lds_dwordx4 v[6:7], off
	v_lshl_add_u64 v[6:7], v[146:147], 0, s[54:55]
	s_mov_b32 m0, s14
	v_readfirstlane_b32 s15, v9
	v_add_u32_e32 v8, 0xe000, v8
	global_load_lds_dwordx4 v[6:7], off
	v_lshl_add_u64 v[6:7], v[148:149], 0, s[54:55]
	s_mov_b32 m0, s15
	v_readfirstlane_b32 s16, v8
	global_load_lds_dwordx4 v[6:7], off
	v_lshl_add_u64 v[6:7], v[150:151], 0, s[54:55]
	s_mov_b32 m0, s16
	v_add_u32_e32 v11, 32, v166
	global_load_lds_dwordx4 v[6:7], off
	v_add_u32_e32 v168, v11, v167
	v_and_b32_e32 v152, 31, v139
	v_lshrrev_b32_e32 v10, 1, v139
	ds_read_b128 v[6:9], v168 offset:32768
	ds_read_b128 v[14:17], v168 offset:36864
	s_mov_b32 s45, 0x1ffff80
	v_and_or_b32 v10, v10, s45, v152
	v_lshlrev_b32_e32 v169, 7, v10
	v_add_u32_e32 v170, v11, v169
	ds_read_b128 v[10:13], v170
	s_waitcnt lgkmcnt(0)
	v_mfma_f32_32x32x16_bf16 v[118:133], v[6:9], v[10:13], 0
	v_bfe_u32 v171, v139, 5, 1
	s_mov_b32 m0, s18
	s_add_i32 s18, 32, 0x18000
	v_add3_u32 v179, s18, v166, v167
	v_add3_u32 v166, s17, v166, v169
	v_mfma_f32_32x32x16_bf16 v[102:117], v[14:17], v[10:13], 0
	ds_read_b128 v[10:13], v170 offset:4096
	s_waitcnt lgkmcnt(0)
	v_mfma_f32_32x32x16_bf16 v[86:101], v[6:9], v[10:13], 0
	v_mfma_f32_32x32x16_bf16 v[70:85], v[14:17], v[10:13], 0
	ds_read_b128 v[10:13], v170 offset:8192
	s_waitcnt lgkmcnt(0)
	v_mfma_f32_32x32x16_bf16 v[54:69], v[6:9], v[10:13], 0
	v_mfma_f32_32x32x16_bf16 v[38:53], v[14:17], v[10:13], 0
	ds_read_b128 v[10:13], v170 offset:12288
	s_waitcnt lgkmcnt(0)
	v_mfma_f32_32x32x16_bf16 v[22:37], v[6:9], v[10:13], 0
	v_bitop3_b32 v6, v171, v153, 2 bitop3:0x36
	v_lshlrev_b32_e32 v172, 4, v6
	v_add_u32_e32 v158, 32, v172
	v_add_u32_e32 v173, v158, v167
	ds_read_b128 v[154:157], v173 offset:32768
	ds_read_b128 v[162:165], v173 offset:36864
	v_add_u32_e32 v174, v158, v169
	ds_read_b128 v[158:161], v174
	s_waitcnt lgkmcnt(0)
	v_mfma_f32_32x32x16_bf16 v[118:133], v[154:157], v[158:161], v[118:133]
	v_add3_u32 v180, s18, v172, v167
	v_add3_u32 v172, s17, v172, v169
	v_mfma_f32_32x32x16_bf16 v[102:117], v[162:165], v[158:161], v[102:117]
	ds_read_b128 v[158:161], v174 offset:4096
	s_waitcnt lgkmcnt(0)
	v_mfma_f32_32x32x16_bf16 v[86:101], v[154:157], v[158:161], v[86:101]
	v_mfma_f32_32x32x16_bf16 v[70:85], v[162:165], v[158:161], v[70:85]
	ds_read_b128 v[158:161], v174 offset:8192
	v_mfma_f32_32x32x16_bf16 v[6:21], v[14:17], v[10:13], 0
	s_waitcnt lgkmcnt(0)
	v_mfma_f32_32x32x16_bf16 v[54:69], v[154:157], v[158:161], v[54:69]
	v_mfma_f32_32x32x16_bf16 v[38:53], v[162:165], v[158:161], v[38:53]
	ds_read_b128 v[158:161], v174 offset:12288
	s_waitcnt lgkmcnt(0)
	v_mfma_f32_32x32x16_bf16 v[22:37], v[154:157], v[158:161], v[22:37]
	v_bitop3_b32 v154, v171, v153, 4 bitop3:0x36
	v_lshlrev_b32_e32 v175, 4, v154
	v_bitop3_b32 v153, v171, v153, 6 bitop3:0x36
	v_lshlrev_b32_e32 v153, 4, v153
	v_add3_u32 v181, s18, v175, v167
	v_mfma_f32_32x32x16_bf16 v[6:21], v[162:165], v[158:161], v[6:21]
	v_add_u32_e32 v158, 32, v175
	v_add_u32_e32 v176, v158, v167
	ds_read_b128 v[154:157], v176 offset:32768
	ds_read_b128 v[162:165], v176 offset:36864
	v_add_u32_e32 v177, v158, v169
	ds_read_b128 v[158:161], v177
	v_add3_u32 v175, s17, v175, v169
	s_waitcnt lgkmcnt(0)
	v_mfma_f32_32x32x16_bf16 v[118:133], v[154:157], v[158:161], v[118:133]
	v_mfma_f32_32x32x16_bf16 v[102:117], v[162:165], v[158:161], v[102:117]
	ds_read_b128 v[158:161], v177 offset:4096
	s_waitcnt lgkmcnt(0)
	v_mfma_f32_32x32x16_bf16 v[86:101], v[154:157], v[158:161], v[86:101]
	v_mfma_f32_32x32x16_bf16 v[70:85], v[162:165], v[158:161], v[70:85]
	ds_read_b128 v[158:161], v177 offset:8192
	s_waitcnt lgkmcnt(0)
	v_mfma_f32_32x32x16_bf16 v[54:69], v[154:157], v[158:161], v[54:69]
	v_mfma_f32_32x32x16_bf16 v[38:53], v[162:165], v[158:161], v[38:53]
	ds_read_b128 v[158:161], v177 offset:12288
	s_waitcnt lgkmcnt(0)
	v_mfma_f32_32x32x16_bf16 v[22:37], v[154:157], v[158:161], v[22:37]
	v_mfma_f32_32x32x16_bf16 v[6:21], v[162:165], v[158:161], v[6:21]
	v_add_u32_e32 v158, 32, v153
	v_add_u32_e32 v171, v158, v167
	ds_read_b128 v[154:157], v171 offset:32768
	ds_read_b128 v[162:165], v171 offset:36864
	v_add_u32_e32 v178, v158, v169
	ds_read_b128 v[158:161], v178
	v_add3_u32 v167, s18, v153, v167
	s_waitcnt lgkmcnt(0)
	v_mfma_f32_32x32x16_bf16 v[118:133], v[154:157], v[158:161], v[118:133]
	v_add3_u32 v153, s17, v153, v169
	v_mfma_f32_32x32x16_bf16 v[102:117], v[162:165], v[158:161], v[102:117]
	ds_read_b128 v[158:161], v178 offset:4096
	s_waitcnt lgkmcnt(0)
	v_mfma_f32_32x32x16_bf16 v[86:101], v[154:157], v[158:161], v[86:101]
	v_mfma_f32_32x32x16_bf16 v[70:85], v[162:165], v[158:161], v[70:85]
	ds_read_b128 v[158:161], v178 offset:8192
	s_waitcnt lgkmcnt(0)
	v_mfma_f32_32x32x16_bf16 v[54:69], v[154:157], v[158:161], v[54:69]
	v_mfma_f32_32x32x16_bf16 v[38:53], v[162:165], v[158:161], v[38:53]
	ds_read_b128 v[158:161], v178 offset:12288
	s_waitcnt vmcnt(0)
	s_waitcnt vmcnt(0) lgkmcnt(0)
	s_barrier
	v_mfma_f32_32x32x16_bf16 v[22:37], v[154:157], v[158:161], v[22:37]
	v_lshl_add_u64 v[154:155], v[0:1], 0, s[96:97]
	global_load_lds_dwordx4 v[154:155], off
	v_lshl_add_u64 v[154:155], v[2:3], 0, s[96:97]
	s_mov_b32 m0, s19
	s_mov_b64 s[18:19], 0x180
	global_load_lds_dwordx4 v[154:155], off
	v_lshl_add_u64 v[154:155], v[134:135], 0, s[96:97]
	s_mov_b32 m0, s20
	v_mfma_f32_32x32x16_bf16 v[6:21], v[162:165], v[158:161], v[6:21]
	global_load_lds_dwordx4 v[154:155], off
	v_lshl_add_u64 v[154:155], v[136:137], 0, s[96:97]
	s_mov_b32 m0, s21
	v_lshl_add_u64 v[0:1], v[0:1], 0, s[18:19]
	global_load_lds_dwordx4 v[154:155], off
	v_lshl_add_u64 v[154:155], v[144:145], 0, s[96:97]
	s_mov_b32 m0, s22
	s_nop 0
	global_load_lds_dwordx4 v[154:155], off
	v_lshl_add_u64 v[154:155], v[146:147], 0, s[96:97]
	s_mov_b32 m0, s23
	s_nop 0
	global_load_lds_dwordx4 v[154:155], off
	v_lshl_add_u64 v[154:155], v[148:149], 0, s[96:97]
	s_mov_b32 m0, s35
	s_nop 0
	global_load_lds_dwordx4 v[154:155], off
	v_lshl_add_u64 v[154:155], v[150:151], 0, s[96:97]
	s_mov_b32 m0, s44
	s_nop 0
	global_load_lds_dwordx4 v[154:155], off
	ds_read_b128 v[154:157], v179
	ds_read_b128 v[158:161], v166
	ds_read_b128 v[162:165], v179 offset:4096
	s_waitcnt lgkmcnt(0)
	v_mfma_f32_32x32x16_bf16 v[118:133], v[154:157], v[158:161], v[118:133]
	s_mov_b32 m0, s1
	s_movk_i32 s1, 0x9f
	v_mfma_f32_32x32x16_bf16 v[102:117], v[162:165], v[158:161], v[102:117]
	ds_read_b128 v[158:161], v166 offset:4096
	s_waitcnt lgkmcnt(0)
	v_mfma_f32_32x32x16_bf16 v[86:101], v[154:157], v[158:161], v[86:101]
	v_mfma_f32_32x32x16_bf16 v[70:85], v[162:165], v[158:161], v[70:85]
	ds_read_b128 v[158:161], v166 offset:8192
	s_waitcnt lgkmcnt(0)
	v_mfma_f32_32x32x16_bf16 v[54:69], v[154:157], v[158:161], v[54:69]
	v_mfma_f32_32x32x16_bf16 v[38:53], v[162:165], v[158:161], v[38:53]
	ds_read_b128 v[158:161], v166 offset:12288
	s_waitcnt lgkmcnt(0)
	v_mfma_f32_32x32x16_bf16 v[22:37], v[154:157], v[158:161], v[22:37]
	ds_read_b128 v[154:157], v180
	v_mfma_f32_32x32x16_bf16 v[6:21], v[162:165], v[158:161], v[6:21]
	ds_read_b128 v[162:165], v180 offset:4096
	ds_read_b128 v[158:161], v172
	s_waitcnt lgkmcnt(0)
	v_mfma_f32_32x32x16_bf16 v[118:133], v[154:157], v[158:161], v[118:133]
	v_mfma_f32_32x32x16_bf16 v[102:117], v[162:165], v[158:161], v[102:117]
	ds_read_b128 v[158:161], v172 offset:4096
	s_waitcnt lgkmcnt(0)
	v_mfma_f32_32x32x16_bf16 v[86:101], v[154:157], v[158:161], v[86:101]
	v_mfma_f32_32x32x16_bf16 v[70:85], v[162:165], v[158:161], v[70:85]
	ds_read_b128 v[158:161], v172 offset:8192
	s_waitcnt lgkmcnt(0)
	v_mfma_f32_32x32x16_bf16 v[54:69], v[154:157], v[158:161], v[54:69]
	v_mfma_f32_32x32x16_bf16 v[38:53], v[162:165], v[158:161], v[38:53]
	ds_read_b128 v[158:161], v172 offset:12288
	s_waitcnt lgkmcnt(0)
	v_mfma_f32_32x32x16_bf16 v[22:37], v[154:157], v[158:161], v[22:37]
	ds_read_b128 v[154:157], v181
	v_mfma_f32_32x32x16_bf16 v[6:21], v[162:165], v[158:161], v[6:21]
	ds_read_b128 v[162:165], v181 offset:4096
	ds_read_b128 v[158:161], v175
	s_waitcnt lgkmcnt(0)
	v_mfma_f32_32x32x16_bf16 v[118:133], v[154:157], v[158:161], v[118:133]
	v_mfma_f32_32x32x16_bf16 v[102:117], v[162:165], v[158:161], v[102:117]
	ds_read_b128 v[158:161], v175 offset:4096
	s_waitcnt lgkmcnt(0)
	v_mfma_f32_32x32x16_bf16 v[86:101], v[154:157], v[158:161], v[86:101]
	v_mfma_f32_32x32x16_bf16 v[70:85], v[162:165], v[158:161], v[70:85]
	ds_read_b128 v[158:161], v175 offset:8192
	s_waitcnt lgkmcnt(0)
	v_mfma_f32_32x32x16_bf16 v[54:69], v[154:157], v[158:161], v[54:69]
	v_mfma_f32_32x32x16_bf16 v[38:53], v[162:165], v[158:161], v[38:53]
	ds_read_b128 v[158:161], v175 offset:12288
	s_waitcnt lgkmcnt(0)
	v_mfma_f32_32x32x16_bf16 v[22:37], v[154:157], v[158:161], v[22:37]
	ds_read_b128 v[154:157], v167
	v_mfma_f32_32x32x16_bf16 v[6:21], v[162:165], v[158:161], v[6:21]
	ds_read_b128 v[162:165], v167 offset:4096
	ds_read_b128 v[158:161], v153
	s_waitcnt lgkmcnt(0)
	v_mfma_f32_32x32x16_bf16 v[118:133], v[154:157], v[158:161], v[118:133]
	v_mfma_f32_32x32x16_bf16 v[102:117], v[162:165], v[158:161], v[102:117]
	ds_read_b128 v[158:161], v153 offset:4096
	s_waitcnt lgkmcnt(0)
	v_mfma_f32_32x32x16_bf16 v[86:101], v[154:157], v[158:161], v[86:101]
	v_mfma_f32_32x32x16_bf16 v[70:85], v[162:165], v[158:161], v[70:85]
	ds_read_b128 v[158:161], v153 offset:8192
	s_waitcnt lgkmcnt(0)
	v_mfma_f32_32x32x16_bf16 v[54:69], v[154:157], v[158:161], v[54:69]
	v_mfma_f32_32x32x16_bf16 v[38:53], v[162:165], v[158:161], v[38:53]
	ds_read_b128 v[158:161], v153 offset:12288
	s_waitcnt vmcnt(0)
	s_waitcnt vmcnt(0) lgkmcnt(0)
	s_barrier
	global_load_lds_dwordx4 v[0:1], off
	v_lshl_add_u64 v[0:1], v[2:3], 0, s[18:19]
	s_mov_b32 m0, s5
	v_mfma_f32_32x32x16_bf16 v[22:37], v[154:157], v[158:161], v[22:37]
	global_load_lds_dwordx4 v[0:1], off
	v_lshl_add_u64 v[0:1], v[134:135], 0, s[18:19]
	s_mov_b32 m0, s6
	s_nop 0
	global_load_lds_dwordx4 v[0:1], off
	v_lshl_add_u64 v[0:1], v[136:137], 0, s[18:19]
	s_mov_b32 m0, s7
	v_mfma_f32_32x32x16_bf16 v[6:21], v[162:165], v[158:161], v[6:21]
	global_load_lds_dwordx4 v[0:1], off
	v_lshl_add_u64 v[0:1], v[144:145], 0, s[18:19]
	s_mov_b32 m0, s13
	s_nop 0
	global_load_lds_dwordx4 v[0:1], off
	v_lshl_add_u64 v[0:1], v[146:147], 0, s[18:19]
	s_mov_b32 m0, s14
	s_nop 0
	global_load_lds_dwordx4 v[0:1], off
	v_lshl_add_u64 v[0:1], v[148:149], 0, s[18:19]
	s_mov_b32 m0, s15
	s_nop 0
	global_load_lds_dwordx4 v[0:1], off
	v_lshl_add_u64 v[0:1], v[150:151], 0, s[18:19]
	s_mov_b32 m0, s16
	s_nop 0
	global_load_lds_dwordx4 v[0:1], off
	ds_read_b128 v[0:3], v168 offset:32768
	ds_read_b128 v[134:137], v170
	ds_read_b128 v[144:147], v168 offset:36864
	s_waitcnt lgkmcnt(0)
	v_mfma_f32_32x32x16_bf16 v[118:133], v[0:3], v[134:137], v[118:133]
	v_mfma_f32_32x32x16_bf16 v[102:117], v[144:147], v[134:137], v[102:117]
	ds_read_b128 v[134:137], v170 offset:4096
	s_waitcnt lgkmcnt(0)
	v_mfma_f32_32x32x16_bf16 v[86:101], v[0:3], v[134:137], v[86:101]
	v_mfma_f32_32x32x16_bf16 v[70:85], v[144:147], v[134:137], v[70:85]
	ds_read_b128 v[134:137], v170 offset:8192
	s_waitcnt lgkmcnt(0)
	v_mfma_f32_32x32x16_bf16 v[54:69], v[0:3], v[134:137], v[54:69]
	v_mfma_f32_32x32x16_bf16 v[38:53], v[144:147], v[134:137], v[38:53]
	ds_read_b128 v[134:137], v170 offset:12288
	s_waitcnt lgkmcnt(0)
	v_mfma_f32_32x32x16_bf16 v[22:37], v[0:3], v[134:137], v[22:37]
	v_mfma_f32_32x32x16_bf16 v[6:21], v[144:147], v[134:137], v[6:21]
	ds_read_b128 v[0:3], v173 offset:32768
	ds_read_b128 v[134:137], v174
	ds_read_b128 v[144:147], v173 offset:36864
	s_waitcnt lgkmcnt(0)
	v_mfma_f32_32x32x16_bf16 v[118:133], v[0:3], v[134:137], v[118:133]
	v_mfma_f32_32x32x16_bf16 v[102:117], v[144:147], v[134:137], v[102:117]
	ds_read_b128 v[134:137], v174 offset:4096
	s_waitcnt lgkmcnt(0)
	v_mfma_f32_32x32x16_bf16 v[86:101], v[0:3], v[134:137], v[86:101]
	v_mfma_f32_32x32x16_bf16 v[70:85], v[144:147], v[134:137], v[70:85]
	ds_read_b128 v[134:137], v174 offset:8192
	s_waitcnt lgkmcnt(0)
	v_mfma_f32_32x32x16_bf16 v[54:69], v[0:3], v[134:137], v[54:69]
	v_mfma_f32_32x32x16_bf16 v[38:53], v[144:147], v[134:137], v[38:53]
	ds_read_b128 v[134:137], v174 offset:12288
	s_waitcnt lgkmcnt(0)
	v_mfma_f32_32x32x16_bf16 v[22:37], v[0:3], v[134:137], v[22:37]
	v_mfma_f32_32x32x16_bf16 v[6:21], v[144:147], v[134:137], v[6:21]
	ds_read_b128 v[0:3], v176 offset:32768
	ds_read_b128 v[134:137], v177
	ds_read_b128 v[144:147], v176 offset:36864
	s_waitcnt lgkmcnt(0)
	v_mfma_f32_32x32x16_bf16 v[118:133], v[0:3], v[134:137], v[118:133]
	v_mfma_f32_32x32x16_bf16 v[102:117], v[144:147], v[134:137], v[102:117]
	ds_read_b128 v[134:137], v177 offset:4096
	s_waitcnt lgkmcnt(0)
	v_mfma_f32_32x32x16_bf16 v[86:101], v[0:3], v[134:137], v[86:101]
	v_mfma_f32_32x32x16_bf16 v[70:85], v[144:147], v[134:137], v[70:85]
	ds_read_b128 v[134:137], v177 offset:8192
	s_waitcnt lgkmcnt(0)
	v_mfma_f32_32x32x16_bf16 v[54:69], v[0:3], v[134:137], v[54:69]
	v_mfma_f32_32x32x16_bf16 v[38:53], v[144:147], v[134:137], v[38:53]
	ds_read_b128 v[134:137], v177 offset:12288
	s_waitcnt lgkmcnt(0)
	v_mfma_f32_32x32x16_bf16 v[22:37], v[0:3], v[134:137], v[22:37]
	v_mfma_f32_32x32x16_bf16 v[6:21], v[144:147], v[134:137], v[6:21]
	ds_read_b128 v[0:3], v171 offset:32768
	ds_read_b128 v[134:137], v178
	ds_read_b128 v[144:147], v171 offset:36864
	s_waitcnt lgkmcnt(0)
	v_mfma_f32_32x32x16_bf16 v[118:133], v[0:3], v[134:137], v[118:133]
	v_mfma_f32_32x32x16_bf16 v[102:117], v[144:147], v[134:137], v[102:117]
	ds_read_b128 v[134:137], v178 offset:4096
	s_waitcnt lgkmcnt(0)
	v_mfma_f32_32x32x16_bf16 v[86:101], v[0:3], v[134:137], v[86:101]
	v_mfma_f32_32x32x16_bf16 v[70:85], v[144:147], v[134:137], v[70:85]
	ds_read_b128 v[134:137], v178 offset:8192
	s_waitcnt lgkmcnt(0)
	v_mfma_f32_32x32x16_bf16 v[54:69], v[0:3], v[134:137], v[54:69]
	v_mfma_f32_32x32x16_bf16 v[38:53], v[144:147], v[134:137], v[38:53]
	ds_read_b128 v[134:137], v178 offset:12288
	s_waitcnt vmcnt(0)
	s_waitcnt vmcnt(0) lgkmcnt(0)
	s_barrier
	v_mfma_f32_32x32x16_bf16 v[22:37], v[0:3], v[134:137], v[22:37]
	v_mfma_f32_32x32x16_bf16 v[6:21], v[144:147], v[134:137], v[6:21]
	ds_read_b128 v[0:3], v179
	ds_read_b128 v[134:137], v166
	ds_read_b128 v[144:147], v179 offset:4096
	s_waitcnt lgkmcnt(1)
	v_mfma_f32_32x32x16_bf16 v[118:133], v[0:3], v[134:137], v[118:133]
	s_waitcnt lgkmcnt(0)
	v_mfma_f32_32x32x16_bf16 v[102:117], v[144:147], v[134:137], v[102:117]
	ds_read_b128 v[134:137], v166 offset:4096
	s_waitcnt lgkmcnt(0)
	v_mfma_f32_32x32x16_bf16 v[86:101], v[0:3], v[134:137], v[86:101]
	v_mfma_f32_32x32x16_bf16 v[70:85], v[144:147], v[134:137], v[70:85]
	ds_read_b128 v[134:137], v166 offset:8192
	s_waitcnt lgkmcnt(0)
	v_mfma_f32_32x32x16_bf16 v[54:69], v[0:3], v[134:137], v[54:69]
	v_mfma_f32_32x32x16_bf16 v[38:53], v[144:147], v[134:137], v[38:53]
	ds_read_b128 v[134:137], v166 offset:12288
	s_waitcnt lgkmcnt(0)
	v_mfma_f32_32x32x16_bf16 v[22:37], v[0:3], v[134:137], v[22:37]
	v_mfma_f32_32x32x16_bf16 v[6:21], v[144:147], v[134:137], v[6:21]
	ds_read_b128 v[0:3], v180
	ds_read_b128 v[134:137], v172
	ds_read_b128 v[144:147], v180 offset:4096
	s_waitcnt lgkmcnt(1)
	v_mfma_f32_32x32x16_bf16 v[118:133], v[0:3], v[134:137], v[118:133]
	s_waitcnt lgkmcnt(0)
	v_mfma_f32_32x32x16_bf16 v[102:117], v[144:147], v[134:137], v[102:117]
	ds_read_b128 v[134:137], v172 offset:4096
	s_waitcnt lgkmcnt(0)
	v_mfma_f32_32x32x16_bf16 v[86:101], v[0:3], v[134:137], v[86:101]
	v_mfma_f32_32x32x16_bf16 v[70:85], v[144:147], v[134:137], v[70:85]
	ds_read_b128 v[134:137], v172 offset:8192
	s_waitcnt lgkmcnt(0)
	v_mfma_f32_32x32x16_bf16 v[54:69], v[0:3], v[134:137], v[54:69]
	v_mfma_f32_32x32x16_bf16 v[38:53], v[144:147], v[134:137], v[38:53]
	ds_read_b128 v[134:137], v172 offset:12288
	s_waitcnt lgkmcnt(0)
	v_mfma_f32_32x32x16_bf16 v[22:37], v[0:3], v[134:137], v[22:37]
	v_mfma_f32_32x32x16_bf16 v[6:21], v[144:147], v[134:137], v[6:21]
	ds_read_b128 v[0:3], v181
	ds_read_b128 v[134:137], v175
	ds_read_b128 v[144:147], v181 offset:4096
	s_waitcnt lgkmcnt(1)
	v_mfma_f32_32x32x16_bf16 v[118:133], v[0:3], v[134:137], v[118:133]
	s_waitcnt lgkmcnt(0)
	v_mfma_f32_32x32x16_bf16 v[102:117], v[144:147], v[134:137], v[102:117]
	ds_read_b128 v[134:137], v175 offset:4096
	s_waitcnt lgkmcnt(0)
	v_mfma_f32_32x32x16_bf16 v[86:101], v[0:3], v[134:137], v[86:101]
	v_mfma_f32_32x32x16_bf16 v[70:85], v[144:147], v[134:137], v[70:85]
	ds_read_b128 v[134:137], v175 offset:8192
	s_waitcnt lgkmcnt(0)
	v_mfma_f32_32x32x16_bf16 v[54:69], v[0:3], v[134:137], v[54:69]
	v_mfma_f32_32x32x16_bf16 v[38:53], v[144:147], v[134:137], v[38:53]
	ds_read_b128 v[134:137], v175 offset:12288
	s_waitcnt lgkmcnt(0)
	v_mfma_f32_32x32x16_bf16 v[22:37], v[0:3], v[134:137], v[22:37]
	v_mfma_f32_32x32x16_bf16 v[6:21], v[144:147], v[134:137], v[6:21]
	ds_read_b128 v[0:3], v167
	ds_read_b128 v[134:137], v153
	ds_read_b128 v[154:157], v167 offset:4096
	ds_read_b128 v[158:161], v153 offset:12288
	v_ashrrev_i32_e32 v144, 1, v139
	v_mov_b64_e32 v[146:147], 0xb152000
	s_waitcnt lgkmcnt(2)
	v_mfma_f32_32x32x16_bf16 v[118:133], v[0:3], v[134:137], v[118:133]
	s_waitcnt lgkmcnt(1)
	v_mfma_f32_32x32x16_bf16 v[102:117], v[154:157], v[134:137], v[102:117]
	ds_read_b128 v[134:137], v153 offset:4096
	s_waitcnt lgkmcnt(0)
	v_mfma_f32_32x32x16_bf16 v[86:101], v[0:3], v[134:137], v[86:101]
	v_mfma_f32_32x32x16_bf16 v[70:85], v[154:157], v[134:137], v[70:85]
	ds_read_b128 v[134:137], v153 offset:8192
	s_waitcnt vmcnt(0)
	s_waitcnt lgkmcnt(0)
	v_mfma_f32_32x32x16_bf16 v[54:69], v[0:3], v[134:137], v[54:69]
	v_mfma_f32_32x32x16_bf16 v[38:53], v[154:157], v[134:137], v[38:53]
	v_and_b32_e32 v134, 0xffffff80, v144
	v_or_b32_e32 v135, v134, v152
	v_lshl_add_u32 v149, s4, 8, v135
	v_bitop3_b32 v136, v134, s1, v152 bitop3:0xc8
	v_ashrrev_i32_e32 v134, 5, v149
	v_and_b32_e32 v148, -8, v134
	v_cmp_lt_i32_e64 s[6:7], s89, v149
	v_mfma_f32_32x32x16_bf16 v[22:37], v[0:3], v[158:161], v[22:37]
	v_add_u32_e32 v0, 0xffffe000, v149
	v_lshrrev_b32_e32 v0, 9, v0
	v_mov_b64_e32 v[2:3], 8
	v_and_b32_e32 v137, 0xf9f, v149
	v_and_b32_e32 v150, 0x7ffff8, v0
	v_mov_b32_e32 v3, v148
	v_mov_b32_e32 v144, v136
	v_mfma_f32_32x32x16_bf16 v[6:21], v[154:157], v[158:161], v[6:21]
	s_and_saveexec_b64 s[4:5], s[6:7]
	v_mov_b64_e32 v[2:3], 12
	v_mov_b64_e32 v[146:147], 0xbd52000
	v_mov_b32_e32 v3, v150
	v_mov_b32_e32 v144, v137
	s_or_b64 exec, exec, s[4:5]
	v_and_b32_e32 v1, 0xc0, v139
	v_lshrrev_b32_e32 v0, 3, v139
	v_lshl_or_b32 v151, s0, 8, v1
	s_mov_b32 s0, 0x2aaaaaab
	v_and_b32_e32 v152, 4, v0
	v_mul_hi_i32 v0, v151, s0
	v_lshrrev_b32_e32 v1, 31, v0
	v_ashrrev_i32_e32 v0, 4, v0
	v_add_u32_e32 v139, v0, v1
	s_movk_i32 s0, 0x60
	v_mul_lo_u32 v0, v139, s0
	v_sub_u32_e32 v134, v151, v0
	v_cmp_eq_u32_e32 vcc, 64, v134
	s_and_b64 s[4:5], s[6:7], vcc
	v_lshlrev_b32_e32 v0, 2, v152
	s_and_saveexec_b64 s[0:1], s[4:5]
	s_cbranch_execz .LBB0_972
	v_readlane_b32 s4, v253, 31
	v_lshlrev_b32_e32 v154, 7, v144
	v_mov_b32_e32 v155, v4
	v_readlane_b32 s5, v253, 32
	v_mov_b32_e32 v1, v4
	s_nop 0
	v_lshl_add_u64 v[156:157], s[4:5], 0, v[154:155]
	v_readlane_b32 s4, v254, 47
	v_readlane_b32 s5, v254, 48
	v_lshl_add_u64 v[162:163], v[156:157], 0, v[0:1]
	s_nop 0
	v_lshl_add_u64 v[154:155], s[4:5], 0, v[154:155]
	v_lshl_add_u64 v[164:165], v[154:155], 0, v[0:1]
	global_load_dwordx4 v[154:157], v[162:163], off
	global_load_dwordx4 v[158:161], v[164:165], off
	s_waitcnt vmcnt(0)
	v_pk_mul_f32 v[166:167], v[122:123], v[158:159]
	s_nop 0
	v_pk_fma_f32 v[166:167], v[118:119], v[154:155], v[166:167] neg_lo:[0,0,1] neg_hi:[0,0,1]
	v_pk_mul_f32 v[118:119], v[118:119], v[158:159]
	s_nop 0
	v_pk_fma_f32 v[122:123], v[122:123], v[154:155], v[118:119]
	v_pk_mul_f32 v[118:119], v[124:125], v[160:161]
	s_nop 0
	v_pk_fma_f32 v[158:159], v[120:121], v[156:157], v[118:119] neg_lo:[0,0,1] neg_hi:[0,0,1]
	v_pk_mul_f32 v[118:119], v[120:121], v[160:161]
	s_nop 0
	v_pk_fma_f32 v[124:125], v[124:125], v[156:157], v[118:119]
	global_load_dwordx4 v[118:121], v[162:163], off offset:64
	global_load_dwordx4 v[154:157], v[164:165], off offset:64
	s_waitcnt vmcnt(0)
	v_pk_mul_f32 v[160:161], v[130:131], v[154:155]
	s_nop 0
	v_pk_fma_f32 v[160:161], v[126:127], v[118:119], v[160:161] neg_lo:[0,0,1] neg_hi:[0,0,1]
	v_pk_mul_f32 v[126:127], v[126:127], v[154:155]
	s_nop 0
	v_pk_fma_f32 v[130:131], v[130:131], v[118:119], v[126:127]
	v_pk_mul_f32 v[118:119], v[132:133], v[156:157]
	v_mov_b32_e32 v126, v160
	v_pk_fma_f32 v[154:155], v[128:129], v[120:121], v[118:119] neg_lo:[0,0,1] neg_hi:[0,0,1]
	v_pk_mul_f32 v[118:119], v[128:129], v[156:157]
	v_mov_b32_e32 v127, v161
	v_pk_fma_f32 v[132:133], v[132:133], v[120:121], v[118:119]
	v_mov_b32_e32 v118, v166
	v_mov_b32_e32 v119, v167
	v_mov_b32_e32 v120, v158
	v_mov_b32_e32 v121, v159
	v_mov_b32_e32 v128, v154
	v_mov_b32_e32 v129, v155

	.amdhsa_kernel _Z8fwd_mega6Params
		.amdhsa_group_segment_fixed_size 20512
		.amdhsa_private_segment_fixed_size 0
		.amdhsa_kernarg_size 448
		.amdhsa_user_sgpr_count 2
		.amdhsa_user_sgpr_dispatch_ptr 0
		.amdhsa_user_sgpr_queue_ptr 0
		.amdhsa_user_sgpr_kernarg_segment_ptr 1
		.amdhsa_user_sgpr_dispatch_id 0
		.amdhsa_user_sgpr_kernarg_preload_length 0
		.amdhsa_user_sgpr_kernarg_preload_offset 0
		.amdhsa_user_sgpr_private_segment_size 0
		.amdhsa_uses_dynamic_stack 0
		.amdhsa_enable_private_segment 0
		.amdhsa_system_sgpr_workgroup_id_x 1
		.amdhsa_system_sgpr_workgroup_id_y 0
		.amdhsa_system_sgpr_workgroup_id_z 0
		.amdhsa_system_sgpr_workgroup_info 0
		.amdhsa_system_vgpr_workitem_id 2
		.amdhsa_next_free_vgpr 256
		.amdhsa_next_free_sgpr 100
		.amdhsa_accum_offset 256
		.amdhsa_reserve_vcc 1
		.amdhsa_float_round_mode_32 0
		.amdhsa_float_round_mode_16_64 0
		.amdhsa_float_denorm_mode_32 3
		.amdhsa_float_denorm_mode_16_64 3
		.amdhsa_dx10_clamp 1
		.amdhsa_ieee_mode 1
		.amdhsa_fp16_overflow 0
		.amdhsa_tg_split 0
		.amdhsa_exception_fp_ieee_invalid_op 0
		.amdhsa_exception_fp_denorm_src 0
		.amdhsa_exception_fp_ieee_div_zero 0
		.amdhsa_exception_fp_ieee_overflow 0
		.amdhsa_exception_fp_ieee_underflow 0
		.amdhsa_exception_fp_ieee_inexact 0
		.amdhsa_exception_int_div_zero 0
	.end_amdhsa_kernel

amdhsa.kernels:
  - .agpr_count:     0
    .args:
      - .offset:         0
        .size:           192
        .value_kind:     by_value
      - .offset:         192
        .size:           4
        .value_kind:     hidden_block_count_x
      - .offset:         196
        .size:           4
        .value_kind:     hidden_block_count_y
      - .offset:         200
        .size:           4
        .value_kind:     hidden_block_count_z
      - .offset:         204
        .size:           2
        .value_kind:     hidden_group_size_x
      - .offset:         206
        .size:           2
        .value_kind:     hidden_group_size_y
      - .offset:         208
        .size:           2
        .value_kind:     hidden_group_size_z
      - .offset:         210
        .size:           2
        .value_kind:     hidden_remainder_x
      - .offset:         212
        .size:           2
        .value_kind:     hidden_remainder_y
      - .offset:         214
        .size:           2
        .value_kind:     hidden_remainder_z
      - .offset:         232
        .size:           8
        .value_kind:     hidden_global_offset_x
      - .offset:         240
        .size:           8
        .value_kind:     hidden_global_offset_y
      - .offset:         248
        .size:           8
        .value_kind:     hidden_global_offset_z
      - .offset:         256
        .size:           2
        .value_kind:     hidden_grid_dims
      - .offset:         280
        .size:           8
        .value_kind:     hidden_multigrid_sync_arg
      - .offset:         312
        .size:           4
        .value_kind:     hidden_dynamic_lds_size
    .group_segment_fixed_size: 20512
    .kernarg_segment_align: 8
    .kernarg_segment_size: 448
    .language:       OpenCL C
    .language_version:
      - 2
      - 0
    .max_flat_workgroup_size: 512
    .name:           _Z8fwd_mega6Params
    .private_segment_fixed_size: 0
    .sgpr_count:     106
    .sgpr_spill_count: 179
    .symbol:         _Z8fwd_mega6Params.kd
    .uniform_work_group_size: 1
    .uses_dynamic_stack: false
    .vgpr_count:     256
    .vgpr_spill_count: 0
    .wavefront_size: 64
